# v25 (full PV ring) + LRU-B conv lone-read hoist + dead RNE leftovers removed
# speedup vs baseline: 1.0027x; 1.0027x over previous
; #define LAS __attribute__((address_space(3)))
; __device__ __forceinline__ unsigned pk2(float lo, float hi) { return f2bf(lo) | (f2bf(hi) << 16); }
; #define MFMA16(a, b, c) __builtin_amdgcn_mfma_f32_16x16x32_bf16(a, b, c, 0, 0, 0)
; __device__ __forceinline__ v4i16_t vtr(const LAS unsigned char* p) { return __builtin_amdgcn_ds_read_tr16_b64_v4i16((LAS v4i16_t*)p); }
; __device__ __forceinline__ void attn_phase(const Params& p, LAS unsigned char* lds, const int bx, const int G, const int tid) {
;     ...
;         const int qi = 16 * wq + fr; float mx = -3e38f;
; #pragma unroll
;         for (int j = 0; j < 9; ++j)
; #pragma unroll
;             for (int e = 0; e < 4; ++e) { const int u = 16 * (wq + j) + 4 * fq + e, jk = X.nb * 64 - 64 + u, dl = u - 64 - qi; const bool ok = jk >= 0 && jk < X.n && dl >= -64 && dl <= 64;
;                 const float b = ((const LAS float*)(L + AT_BIAS))[ok ? dl + 64 : 0]; const float sv = ok ? st[j][e] + b : -1e30f; st[j][e] = sv; mx = fmaxf(mx, sv); }
;         mx = fmaxf(mx, __shfl_xor(mx, 16)); mx = fmaxf(mx, __shfl_xor(mx, 32));
;         float sm = 0.f;
; #pragma unroll
;         for (int j = 0; j < 9; ++j)
; #pragma unroll
;             for (int e = 0; e < 4; ++e) { const float pv = __expf(st[j][e] - mx); st[j][e] = pv; sm += pv; }
;         sm += __shfl_xor(sm, 16); sm += __shfl_xor(sm, 32);
;         f32x4 ot[4];
; #pragma unroll
;         for (int dt = 0; dt < 4; ++dt) ot[dt] = (f32x4){0.f, 0.f, 0.f, 0.f};
; #pragma unroll
;         for (int ks = 0; ks < 5; ++ks) { v4u pw; pw.x = pk2(st[2 * ks][0], st[2 * ks][1]); pw.y = pk2(st[2 * ks][2], st[2 * ks][3]); pw.z = pk2(st[2 * ks + 1][0], st[2 * ks + 1][1]); pw.w = pk2(st[2 * ks + 1][2], st[2 * ks + 1][3]);
;             const bf16x8 pb = __builtin_bit_cast(bf16x8, pw);
; #pragma unroll
;             for (int dt = 0; dt < 4; ++dt) { const LAS unsigned char* vr = vbp + ks * 5120 + dt * 32;
;                 const v4i16_t lo = vtr(vr), hi = vtr(vr + 16 * 160);
;                 ot[dt] = MFMA16(__builtin_shufflevector(lo, hi, 0, 1, 2, 3, 4, 5, 6, 7), pb, ot[dt]); } }
.LBB0_487:
	s_or_b64 exec, exec, s[12:13]
	s_mov_b32 s2, 0xff61b1e6
	v_max3_f32 v60, v66, s2, v65
	v_max3_f32 v60, v60, v96, v67
	v_max3_f32 v60, v60, v98, v97
	v_max3_f32 v60, v60, v93, v92
	v_max3_f32 v60, v60, v95, v94
	v_max3_f32 v60, v60, v89, v88
	v_max3_f32 v60, v60, v91, v90
	v_max3_f32 v60, v60, v85, v84
	v_max3_f32 v60, v60, v87, v86
	v_max3_f32 v60, v60, v99, v80
	v_max3_f32 v60, v60, v82, v81
	v_max3_f32 v60, v60, v83, v76
	v_max3_f32 v60, v60, v188, v187
	v_max3_f32 v60, v60, v73, v72
	v_max3_f32 v60, v60, v75, v74
	v_max3_f32 v60, v60, v190, v68
	v_max3_f32 v60, v60, v192, v191
	v_max3_f32 v60, v60, v195, v194
	ds_bpermute_b32 v62, v122, v60
	s_lshl_b32 s12, s37, 6
	s_add_i32 s13, s12, 0x7fffc000
	s_and_b32 s13, s13, 0x7ffff800
	s_and_b32 s50, s56, s86
	s_waitcnt lgkmcnt(0)
	v_max_f32_e32 v62, v62, v62
	v_max_f32_e32 v60, v60, v62
	ds_bpermute_b32 v62, v123, v60
	s_add_i32 s37, s13, 0x4000
	s_and_b32 s51, s12, 0x2000
	s_and_b64 s[12:13], s[40:41], exec
	s_cselect_b32 s13, 7, 5
	s_waitcnt lgkmcnt(0)
	v_max_f32_e32 v62, v62, v62
	v_max_f32_e32 v60, v60, v62
	v_sub_f32_e32 v63, v65, v60
	v_mul_f32_e32 v63, 0x3fb8aa3b, v63
	v_exp_f32_e32 v107, v63
	v_sub_f32_e32 v63, v96, v60
	v_mul_f32_e32 v63, 0x3fb8aa3b, v63
	v_exp_f32_e32 v96, v63
	v_sub_f32_e32 v63, v67, v60
	v_mul_f32_e32 v63, 0x3fb8aa3b, v63
	v_exp_f32_e32 v150, v63
	v_sub_f32_e32 v63, v98, v60
	v_mul_f32_e32 v63, 0x3fb8aa3b, v63
	v_exp_f32_e32 v98, v63
	v_sub_f32_e32 v63, v97, v60
	v_mul_f32_e32 v63, 0x3fb8aa3b, v63
	v_exp_f32_e32 v97, v63
	v_sub_f32_e32 v63, v93, v60
	v_mul_f32_e32 v63, 0x3fb8aa3b, v63
	v_exp_f32_e32 v151, v63
	v_sub_f32_e32 v63, v92, v60
	v_mul_f32_e32 v63, 0x3fb8aa3b, v63
	v_exp_f32_e32 v152, v63
	v_sub_f32_e32 v63, v95, v60
	v_mul_f32_e32 v63, 0x3fb8aa3b, v63
	v_exp_f32_e32 v92, v63
	v_sub_f32_e32 v63, v94, v60
	v_mul_f32_e32 v63, 0x3fb8aa3b, v63
	v_exp_f32_e32 v93, v63
	v_sub_f32_e32 v63, v89, v60
	v_sub_f32_e32 v62, v66, v60
	v_mul_f32_e32 v63, 0x3fb8aa3b, v63
	v_mul_f32_e32 v62, 0x3fb8aa3b, v62
	v_exp_f32_e32 v89, v63
	v_sub_f32_e32 v63, v88, v60
	v_exp_f32_e32 v105, v62
	v_mul_f32_e32 v63, 0x3fb8aa3b, v63
	v_exp_f32_e32 v88, v63
	v_sub_f32_e32 v63, v91, v60
	v_mul_f32_e32 v63, 0x3fb8aa3b, v63
	v_exp_f32_e32 v91, v63
	v_sub_f32_e32 v63, v90, v60
	v_add_f32_e32 v62, 0, v105
	v_mul_f32_e32 v63, 0x3fb8aa3b, v63
	v_add_f32_e32 v62, v107, v62
	v_exp_f32_e32 v90, v63
	v_sub_f32_e32 v63, v85, v60
	v_add_f32_e32 v62, v96, v62
	v_mul_f32_e32 v63, 0x3fb8aa3b, v63
	v_add_f32_e32 v62, v150, v62
	v_exp_f32_e32 v85, v63
	v_sub_f32_e32 v63, v84, v60
	v_add_f32_e32 v62, v98, v62
	v_mul_f32_e32 v63, 0x3fb8aa3b, v63
	v_add_f32_e32 v62, v97, v62
	v_exp_f32_e32 v196, v63
	v_sub_f32_e32 v63, v87, v60
	v_add_f32_e32 v62, v151, v62
	v_mul_f32_e32 v63, 0x3fb8aa3b, v63
	v_add_f32_e32 v62, v152, v62
	v_exp_f32_e32 v77, v63
	v_sub_f32_e32 v63, v86, v60
	v_add_f32_e32 v62, v92, v62
	v_mul_f32_e32 v63, 0x3fb8aa3b, v63
	v_bfe_u32 v87, v97, 16, 1
	v_bfe_u32 v95, v107, 16, 1
	v_add_f32_e32 v62, v93, v62
	v_exp_f32_e32 v79, v63
	v_sub_f32_e32 v63, v99, v60
	v_add3_u32 v99, v107, v95, s33
	v_add3_u32 v87, v97, v87, s33
	v_bfe_u32 v95, v105, 16, 1
	v_bfe_u32 v97, v96, 16, 1
	v_bfe_u32 v107, v98, 16, 1
	v_add_f32_e32 v62, v89, v62
	v_bfe_u32 v94, v150, 16, 1
	v_add3_u32 v98, v98, v107, s33
	v_add3_u32 v96, v96, v97, s33
	v_add3_u32 v95, v105, v95, s33
	v_add_f32_e32 v62, v88, v62
	v_add3_u32 v94, v150, v94, s33
	v_bfe_u32 v150, v151, 16, 1
	v_lshrrev_b32_e32 v105, 16, v95
	v_lshrrev_b32_e32 v95, 16, v96
	v_lshrrev_b32_e32 v96, 16, v98
	v_add_f32_e32 v62, v91, v62
	v_bfe_u32 v86, v152, 16, 1
	v_add3_u32 v150, v151, v150, s33
	v_and_or_b32 v96, v87, s11, v96
	v_and_or_b32 v95, v94, s11, v95
	v_and_or_b32 v94, v99, s11, v105
	v_bfe_u32 v87, v90, 16, 1
	v_bfe_u32 v98, v88, 16, 1
	v_bfe_u32 v99, v93, 16, 1
	v_add_f32_e32 v62, v90, v62
	v_add3_u32 v86, v152, v86, s33
	v_lshrrev_b32_e32 v97, 16, v150
	ds_read_b64_tr_b16 v[152:153], v186 offset:30208
	ds_read_b64_tr_b16 v[150:151], v186 offset:27648
	ds_read_b64_tr_b16 v[198:199], v186 offset:27680
	ds_read_b64_tr_b16 v[200:201], v186 offset:30240
	v_add3_u32 v93, v93, v99, s33
	v_add3_u32 v98, v88, v98, s33
	v_add3_u32 v87, v90, v87, s33
	v_bfe_u32 v88, v92, 16, 1
	v_bfe_u32 v90, v89, 16, 1
	v_bfe_u32 v99, v91, 16, 1
	v_bfe_u32 v105, v85, 16, 1
	v_add_f32_e32 v62, v85, v62
	v_and_or_b32 v97, v86, s11, v97
	v_add3_u32 v91, v91, v99, s33
	v_add3_u32 v89, v89, v90, s33
	v_add3_u32 v88, v92, v88, s33
	v_lshrrev_b32_e32 v90, 16, v88
	v_lshrrev_b32_e32 v92, 16, v89
	v_lshrrev_b32_e32 v88, 16, v91
	ds_read_b64_tr_b16 v[202:203], v186 offset:27712
	ds_read_b64_tr_b16 v[204:205], v186 offset:30272
	ds_read_b64_tr_b16 v[206:207], v186 offset:27744
	ds_read_b64_tr_b16 v[208:209], v186 offset:30304
	v_cvt_pk_bf16_f32 v89, v85, v196
	v_and_or_b32 v88, v87, s11, v88
	v_and_or_b32 v87, v98, s11, v92
	v_and_or_b32 v86, v93, s11, v90
	ds_read_b64_tr_b16 v[90:91], v186 offset:32768
	ds_read_b64_tr_b16 v[92:93], v186 offset:35328
	ds_read_b64_tr_b16 v[236:237], v186 offset:32800
	ds_read_b64_tr_b16 v[238:239], v186 offset:35360
	ds_read_b64_tr_b16 v[246:247], v186 offset:32832
	ds_read_b64_tr_b16 v[248:249], v186 offset:35392
	ds_read_b64_tr_b16 v[210:211], v186 offset:32864
	ds_read_b64_tr_b16 v[212:213], v186 offset:35424
	s_waitcnt lgkmcnt(14)
	v_mfma_f32_16x16x32_bf16 v[150:153], v[150:153], v[94:97], 0
	v_mul_f32_e32 v63, 0x3fb8aa3b, v63
	v_exp_f32_e32 v78, v63
	v_sub_f32_e32 v63, v80, v60
	s_waitcnt lgkmcnt(6)
; #define LAS __attribute__((address_space(3)))
; __device__ __forceinline__ unsigned pk2(float lo, float hi) { return f2bf(lo) | (f2bf(hi) << 16); }
; #define MFMA16(a, b, c) __builtin_amdgcn_mfma_f32_16x16x32_bf16(a, b, c, 0, 0, 0)
; __device__ __forceinline__ v4i16_t vtr(const LAS unsigned char* p) { return __builtin_amdgcn_ds_read_tr16_b64_v4i16((LAS v4i16_t*)p); }
; __device__ __forceinline__ void attn_phase(const Params& p, LAS unsigned char* lds, const int bx, const int G, const int tid) {
;     ...
; #pragma unroll
;         for (int j = 0; j < 9; ++j)
; #pragma unroll
;             for (int e = 0; e < 4; ++e) { const float pv = __expf(st[j][e] - mx); st[j][e] = pv; sm += pv; }
;         sm += __shfl_xor(sm, 16); sm += __shfl_xor(sm, 32);
;         f32x4 ot[4];
; #pragma unroll
;         for (int dt = 0; dt < 4; ++dt) ot[dt] = (f32x4){0.f, 0.f, 0.f, 0.f};
; #pragma unroll
;         for (int ks = 0; ks < 5; ++ks) { v4u pw; pw.x = pk2(st[2 * ks][0], st[2 * ks][1]); pw.y = pk2(st[2 * ks][2], st[2 * ks][3]); pw.z = pk2(st[2 * ks + 1][0], st[2 * ks + 1][1]); pw.w = pk2(st[2 * ks + 1][2], st[2 * ks + 1][3]);
;             const bf16x8 pb = __builtin_bit_cast(bf16x8, pw);
; #pragma unroll
;             for (int dt = 0; dt < 4; ++dt) { const LAS unsigned char* vr = vbp + ks * 5120 + dt * 32;
;                 const v4i16_t lo = vtr(vr), hi = vtr(vr + 16 * 160);
;                 ot[dt] = MFMA16(__builtin_shufflevector(lo, hi, 0, 1, 2, 3, 4, 5, 6, 7), pb, ot[dt]); } }
	v_mfma_f32_16x16x32_bf16 v[90:93], v[90:93], v[86:89], v[150:153]
	s_nop 2
	ds_read_b64_tr_b16 v[214:215], v186 offset:37888
	ds_read_b64_tr_b16 v[216:217], v186 offset:40448
	v_mul_f32_e32 v63, 0x3fb8aa3b, v63
	v_exp_f32_e32 v80, v63
	v_mfma_f32_16x16x32_bf16 v[198:201], v[198:201], v[94:97], 0
	v_sub_f32_e32 v63, v82, v60
	v_mul_f32_e32 v63, 0x3fb8aa3b, v63
	v_exp_f32_e32 v82, v63
	s_waitcnt lgkmcnt(6)
	v_mfma_f32_16x16x32_bf16 v[150:153], v[236:239], v[86:89], v[198:201]
	s_nop 2
	ds_read_b64_tr_b16 v[218:219], v186 offset:37920
	ds_read_b64_tr_b16 v[220:221], v186 offset:40480
	v_sub_f32_e32 v63, v81, v60
	v_mul_f32_e32 v63, 0x3fb8aa3b, v63
	v_mfma_f32_16x16x32_bf16 v[202:205], v[202:205], v[94:97], 0
	v_exp_f32_e32 v81, v63
	v_sub_f32_e32 v63, v83, v60
	v_add_f32_e32 v62, v196, v62
	v_mul_f32_e32 v63, 0x3fb8aa3b, v63
	s_waitcnt lgkmcnt(6)
	v_mfma_f32_16x16x32_bf16 v[198:201], v[246:249], v[86:89], v[202:205]
	s_nop 2
	ds_read_b64_tr_b16 v[222:223], v186 offset:37952
	ds_read_b64_tr_b16 v[224:225], v186 offset:40512
	v_add_f32_e32 v62, v77, v62
	v_exp_f32_e32 v83, v63
	v_sub_f32_e32 v63, v76, v60
	v_mfma_f32_16x16x32_bf16 v[94:97], v[206:209], v[94:97], 0
	v_add_f32_e32 v62, v79, v62
	v_mul_f32_e32 v63, 0x3fb8aa3b, v63
	v_add_f32_e32 v62, v78, v62
	v_exp_f32_e32 v84, v63
	v_add_f32_e32 v62, v80, v62
	v_add_f32_e32 v62, v82, v62
	s_waitcnt lgkmcnt(6)
	v_mfma_f32_16x16x32_bf16 v[86:89], v[210:213], v[86:89], v[94:97]
	ds_read_b64_tr_b16 v[226:227], v186 offset:37984
	ds_read_b64_tr_b16 v[228:229], v186 offset:40544
	v_add_f32_e32 v62, v81, v62
	v_sub_f32_e32 v63, v188, v60
	v_add_f32_e32 v62, v83, v62
	v_bfe_u32 v94, v81, 16, 1
	v_bfe_u32 v95, v80, 16, 1
	v_bfe_u32 v96, v79, 16, 1
	v_add3_u32 v96, v79, v96, s33
	v_add3_u32 v79, v80, v95, s33
	v_add3_u32 v80, v81, v94, s33
	v_bfe_u32 v94, v82, 16, 1
	v_bfe_u32 v95, v83, 16, 1
	v_mul_f32_e32 v63, 0x3fb8aa3b, v63
	v_bfe_u32 v85, v84, 16, 1
	v_add3_u32 v83, v83, v95, s33
	v_add3_u32 v82, v82, v94, s33
	v_add_f32_e32 v62, v84, v62
	v_exp_f32_e32 v69, v63
	v_sub_f32_e32 v63, v187, v60
	v_add3_u32 v81, v84, v85, s33
	v_bfe_u32 v84, v77, 16, 1
	v_bfe_u32 v85, v78, 16, 1
	v_lshrrev_b32_e32 v82, 16, v82
	v_lshrrev_b32_e32 v83, 16, v83
	v_mul_f32_e32 v63, 0x3fb8aa3b, v63
	v_add3_u32 v78, v78, v85, s33
	v_add3_u32 v77, v77, v84, s33
	v_and_or_b32 v81, v81, s11, v83
	v_and_or_b32 v80, v80, s11, v82
	ds_read_b64_tr_b16 v[236:237], v186 offset:43008
	ds_read_b64_tr_b16 v[238:239], v186 offset:45568
	v_exp_f32_e32 v71, v63
	v_sub_f32_e32 v63, v73, v60
	v_mul_f32_e32 v63, 0x3fb8aa3b, v63
	v_exp_f32_e32 v70, v63
	v_sub_f32_e32 v63, v72, v60
	v_lshrrev_b32_e32 v77, 16, v77
	v_lshrrev_b32_e32 v78, 16, v78
	v_mul_f32_e32 v63, 0x3fb8aa3b, v63
	v_and_or_b32 v79, v79, s11, v78
	v_and_or_b32 v78, v96, s11, v77
	v_exp_f32_e32 v73, v63
	v_sub_f32_e32 v63, v75, v60
	s_waitcnt lgkmcnt(8)
	v_mfma_f32_16x16x32_bf16 v[82:85], v[214:217], v[78:81], v[90:93]
	s_nop 2
	ds_read_b64_tr_b16 v[246:247], v186 offset:43040
	ds_read_b64_tr_b16 v[248:249], v186 offset:45600
	v_mul_f32_e32 v63, 0x3fb8aa3b, v63
	v_exp_f32_e32 v72, v63
	v_sub_f32_e32 v63, v74, v60
	v_mul_f32_e32 v63, 0x3fb8aa3b, v63
	v_exp_f32_e32 v75, v63
	v_sub_f32_e32 v63, v190, v60
	v_mul_f32_e32 v63, 0x3fb8aa3b, v63
	s_waitcnt lgkmcnt(8)
	v_mfma_f32_16x16x32_bf16 v[90:93], v[218:221], v[78:81], v[150:153]
	ds_read_b64_tr_b16 v[210:211], v186 offset:43072
	ds_read_b64_tr_b16 v[212:213], v186 offset:45632
	s_nop 0
	ds_read_b64_tr_b16 v[214:215], v186 offset:43104
	ds_read_b64_tr_b16 v[216:217], v186 offset:45664
	v_add_f32_e32 v62, v69, v62
	v_exp_f32_e32 v74, v63
	v_sub_f32_e32 v63, v68, v60
	v_add_f32_e32 v62, v71, v62
	v_mul_f32_e32 v63, 0x3fb8aa3b, v63
	v_add_f32_e32 v62, v70, v62
	v_exp_f32_e32 v76, v63
	v_add_f32_e32 v62, v73, v62
	v_add_f32_e32 v62, v72, v62
	s_waitcnt lgkmcnt(10)
	v_mfma_f32_16x16x32_bf16 v[94:97], v[222:225], v[78:81], v[198:201]
	v_add_f32_e32 v62, v75, v62
	v_add_f32_e32 v62, v74, v62
	v_bfe_u32 v77, v76, 16, 1
	s_waitcnt lgkmcnt(8)
	v_mfma_f32_16x16x32_bf16 v[78:81], v[226:229], v[78:81], v[86:89]
	v_add_f32_e32 v62, v76, v62
	v_sub_f32_e32 v63, v192, v60
	v_mul_f32_e32 v63, 0x3fb8aa3b, v63
	v_bfe_u32 v86, v75, 16, 1
	v_bfe_u32 v87, v73, 16, 1
	v_bfe_u32 v88, v71, 16, 1
	v_add3_u32 v88, v71, v88, s33
	v_add3_u32 v71, v73, v87, s33
	v_bfe_u32 v87, v74, 16, 1
	v_add3_u32 v74, v74, v87, s33
	v_add3_u32 v73, v76, v77, s33
	v_bfe_u32 v76, v69, 16, 1
	v_bfe_u32 v77, v70, 16, 1
	v_lshrrev_b32_e32 v74, 16, v74
	v_add3_u32 v70, v70, v77, s33
	v_add3_u32 v69, v69, v76, s33
	v_and_or_b32 v73, v73, s11, v74
	v_cvt_pk_bf16_f32 v72, v72, v75
	ds_read_b64_tr_b16 v[218:219], v186 offset:48128
	ds_read_b64_tr_b16 v[220:221], v186 offset:50688
	v_lshrrev_b32_e32 v69, 16, v69
	v_lshrrev_b32_e32 v70, 16, v70
	v_and_or_b32 v71, v71, s11, v70
	v_and_or_b32 v70, v88, s11, v69
	v_exp_f32_e32 v66, v63
	v_sub_f32_e32 v63, v191, v60
	s_waitcnt lgkmcnt(8)
; #define LAS __attribute__((address_space(3)))
; __device__ __forceinline__ unsigned pk2(float lo, float hi) { return f2bf(lo) | (f2bf(hi) << 16); }
; #define MFMA16(a, b, c) __builtin_amdgcn_mfma_f32_16x16x32_bf16(a, b, c, 0, 0, 0)
; __device__ __forceinline__ v4i16_t vtr(const LAS unsigned char* p) { return __builtin_amdgcn_ds_read_tr16_b64_v4i16((LAS v4i16_t*)p); }
; __device__ __forceinline__ void attn_phase(const Params& p, LAS unsigned char* lds, const int bx, const int G, const int tid) {
;     ...
; #pragma unroll
;         for (int j = 0; j < 9; ++j)
; #pragma unroll
;             for (int e = 0; e < 4; ++e) { const float pv = __expf(st[j][e] - mx); st[j][e] = pv; sm += pv; }
;         sm += __shfl_xor(sm, 16); sm += __shfl_xor(sm, 32);
;         f32x4 ot[4];
; #pragma unroll
;         for (int dt = 0; dt < 4; ++dt) ot[dt] = (f32x4){0.f, 0.f, 0.f, 0.f};
; #pragma unroll
;         for (int ks = 0; ks < 5; ++ks) { v4u pw; pw.x = pk2(st[2 * ks][0], st[2 * ks][1]); pw.y = pk2(st[2 * ks][2], st[2 * ks][3]); pw.z = pk2(st[2 * ks + 1][0], st[2 * ks + 1][1]); pw.w = pk2(st[2 * ks + 1][2], st[2 * ks + 1][3]);
;             const bf16x8 pb = __builtin_bit_cast(bf16x8, pw);
; #pragma unroll
;             for (int dt = 0; dt < 4; ++dt) { const LAS unsigned char* vr = vbp + ks * 5120 + dt * 32;
;                 const v4i16_t lo = vtr(vr), hi = vtr(vr + 16 * 160);
;                 ot[dt] = MFMA16(__builtin_shufflevector(lo, hi, 0, 1, 2, 3, 4, 5, 6, 7), pb, ot[dt]); } }
;         { const size_t m = (size_t)(X.m0 + (X.nb * 64 + qi) * d + X.r); const float inv = 1.f / sm;
; #pragma unroll
;           for (int dt = 0; dt < 4; ++dt) { unsigned long long w = (unsigned long long)pk2(ot[dt][0] * inv, ot[dt][1] * inv) | ((unsigned long long)pk2(ot[dt][2] * inv, ot[dt][3] * inv) << 32);
	v_mfma_f32_16x16x32_bf16 v[74:77], v[236:239], v[70:73], v[82:85]
	s_nop 2
	ds_read_b64_tr_b16 v[222:223], v186 offset:48160
	ds_read_b64_tr_b16 v[224:225], v186 offset:50720
	v_mul_f32_e32 v63, 0x3fb8aa3b, v63
	v_exp_f32_e32 v65, v63
	v_sub_f32_e32 v63, v195, v60
	v_mul_f32_e32 v63, 0x3fb8aa3b, v63
	v_exp_f32_e32 v67, v63
	v_sub_f32_e32 v63, v194, v60
	s_waitcnt lgkmcnt(8)
	v_mfma_f32_16x16x32_bf16 v[82:85], v[246:249], v[70:73], v[90:93]
	ds_read_b64_tr_b16 v[226:227], v186 offset:48192
	ds_read_b64_tr_b16 v[228:229], v186 offset:50752
	s_nop 0
	ds_read_b64_tr_b16 v[236:237], v186 offset:48224
	ds_read_b64_tr_b16 v[238:239], v186 offset:50784
	v_mul_f32_e32 v63, 0x3fb8aa3b, v63
	v_exp_f32_e32 v68, v63
	v_add_f32_e32 v62, v66, v62
	v_add_f32_e32 v62, v65, v62
	v_add_f32_e32 v62, v67, v62
	s_waitcnt lgkmcnt(10)
	v_mfma_f32_16x16x32_bf16 v[86:89], v[210:213], v[70:73], v[94:97]
	v_add_f32_e32 v62, v68, v62
	ds_bpermute_b32 v63, v122, v62
	v_and_b32_sdwa v69, v67, v189 dst_sel:DWORD dst_unused:UNUSED_PAD src0_sel:WORD_1 src1_sel:DWORD
	s_waitcnt lgkmcnt(9)
	v_mfma_f32_16x16x32_bf16 v[70:73], v[214:217], v[70:73], v[78:81]
	v_add3_u32 v67, v67, v69, s33
	v_and_b32_sdwa v69, v68, v189 dst_sel:DWORD dst_unused:UNUSED_PAD src0_sel:WORD_1 src1_sel:DWORD
	v_add3_u32 v68, v68, v69, s33
	v_and_b32_sdwa v78, v66, v189 dst_sel:DWORD dst_unused:UNUSED_PAD src0_sel:WORD_1 src1_sel:DWORD
	v_add3_u32 v66, v66, v78, s33
	v_and_b32_sdwa v78, v65, v189 dst_sel:DWORD dst_unused:UNUSED_PAD src0_sel:WORD_1 src1_sel:DWORD
	v_add3_u32 v65, v65, v78, s33
	v_and_b32_e32 v68, 0xffff0000, v68
	v_and_b32_e32 v65, 0xffff0000, v65
	v_or_b32_sdwa v67, v68, v67 dst_sel:DWORD dst_unused:UNUSED_PAD src0_sel:DWORD src1_sel:WORD_1
	v_or_b32_sdwa v66, v65, v66 dst_sel:DWORD dst_unused:UNUSED_PAD src0_sel:DWORD src1_sel:WORD_1
	v_mov_b32_e32 v68, v0
	v_mov_b32_e32 v69, v0
	s_waitcnt lgkmcnt(0)
	v_add_f32_e32 v62, v62, v63
	ds_bpermute_b32 v63, v123, v62
	s_waitcnt lgkmcnt(1)
	v_mfma_f32_16x16x32_bf16 v[74:77], v[218:221], v[66:69], v[74:77]
	v_sub_u32_e32 v61, s13, v3
	s_cselect_b32 s12, s51, s37
	v_lshrrev_b32_e64 v61, v61, s50
	s_waitcnt lgkmcnt(0)
	v_mfma_f32_16x16x32_bf16 v[78:81], v[222:225], v[66:69], v[82:85]
	s_nop 2
	v_add_f32_e32 v62, v62, v63
	v_or_b32_e32 v63, v64, v121
	v_or_b32_e32 v61, s12, v61
	v_lshl_add_u32 v61, v63, v3, v61
	v_div_scale_f32 v3, s[12:13], v62, v62, 1.0
	v_rcp_f32_e32 v63, v3
	s_waitcnt lgkmcnt(0)
	v_mfma_f32_16x16x32_bf16 v[82:85], v[226:229], v[66:69], v[86:89]
	s_nop 2
	v_mov_b32_e32 v107, v0
	v_fma_f32 v64, -v3, v63, 1.0
	v_fmac_f32_e32 v63, v64, v63
	v_div_scale_f32 v64, vcc, 1.0, v62, 1.0
	v_mul_f32_e32 v65, v64, v63
	s_waitcnt lgkmcnt(0)
	v_mfma_f32_16x16x32_bf16 v[66:69], v[236:239], v[66:69], v[70:73]
	v_readlane_b32 s2, v254, 55
	v_readlane_b32 s3, v254, 56
	s_nop 0
	v_fma_f32 v70, -v3, v65, v64
	v_fmac_f32_e32 v65, v70, v63
	v_fma_f32 v3, -v3, v65, v64
	v_div_fmas_f32 v3, v3, v63, v65
	v_div_fixup_f32 v3, v3, v62, 1.0
	v_mov_b64_e32 v[64:65], s[90:91]
	v_lshlrev_b32_e32 v70, 6, v2
	v_mad_i64_i32 v[64:65], s[12:13], v61, s57, v[64:65]
	v_ashrrev_i32_e32 v71, 31, v70
	v_mul_f32_e32 v63, v3, v74
	v_lshl_add_u64 v[64:65], v[70:71], 1, v[64:65]
	v_mul_f32_e32 v70, v3, v75
	v_cvt_pk_bf16_f32 v70, v63, v70
	v_mul_f32_e32 v63, v3, v76
	v_mul_f32_e32 v71, v3, v77
	v_lshl_add_u64 v[64:65], v[64:65], 0, v[106:107]
	v_cvt_pk_bf16_f32 v71, v63, v71
	v_mul_f32_e32 v63, v3, v78
	global_store_dwordx2 v[64:65], v[70:71], off
	v_mul_f32_e32 v70, v3, v79
	v_cvt_pk_bf16_f32 v70, v63, v70
	v_mul_f32_e32 v63, v3, v80
	v_mul_f32_e32 v71, v3, v81
	v_cvt_pk_bf16_f32 v71, v63, v71
	v_mul_f32_e32 v63, v3, v82
	global_store_dwordx2 v[64:65], v[70:71], off offset:32
	v_mul_f32_e32 v70, v3, v83
	v_cvt_pk_bf16_f32 v70, v63, v70
	v_mul_f32_e32 v63, v3, v84
	v_mul_f32_e32 v71, v3, v85
	v_bfe_u32 v72, v71, 16, 1
	v_cvt_pk_bf16_f32 v71, v63, v71
	v_mul_f32_e32 v63, v3, v66
	v_mul_f32_e32 v66, v3, v67
	v_cvt_pk_bf16_f32 v66, v63, v66
	v_mul_f32_e32 v63, v3, v68
	v_mul_f32_e32 v3, v3, v69
	v_bfe_u32 v67, v63, 16, 1
	v_add3_u32 v63, v63, v67, s33
	v_bfe_u32 v67, v3, 16, 1
	v_lshrrev_b32_e32 v63, 16, v63
	v_add3_u32 v3, v3, v67, s33
	v_and_or_b32 v67, v3, s11, v63
	global_store_dwordx2 v[64:65], v[70:71], off offset:64
	global_store_dwordx2 v[64:65], v[66:67], off offset:96
	s_and_saveexec_b64 s[12:13], s[2:3]
	s_cbranch_execz .LBB0_386
	s_mov_b32 s37, 0x800000
	v_cmp_gt_f32_e32 vcc, s37, v62
	s_mov_b32 s37, 0x3f317217
	s_mov_b32 s2, 0x7f800000
	v_cndmask_b32_e64 v3, 0, 32, vcc
	v_ldexp_f32 v3, v62, v3
	v_log_f32_e32 v3, v3
	v_cndmask_b32_e32 v62, 0, v233, vcc
	v_mul_f32_e32 v63, 0x3f317217, v3
	v_fma_f32 v63, v3, s37, -v63
	v_fmac_f32_e32 v63, 0x3377d1cf, v3
	v_fmac_f32_e32 v63, 0x3f317217, v3
	v_cmp_lt_f32_e64 vcc, |v3|, s2
	v_readlane_b32 s2, v253, 7
	v_readlane_b32 s3, v253, 8
	v_cndmask_b32_e32 v3, v3, v63, vcc
	v_sub_f32_e32 v3, v3, v62
	v_add_f32_e32 v62, v60, v3
	v_ashrrev_i32_e32 v3, 31, v2
	v_mad_i64_i32 v[60:61], s[40:41], v61, 48, s[2:3]
	v_lshl_add_u64 v[2:3], v[2:3], 2, v[60:61]
	global_store_dword v[2:3], v62, off
	s_branch .LBB0_386
